# v7 + attention: lane address hoist and f32 row sums kept as packed partial sums (one v_pk_add_f32 per exp pair)
# baseline (speedup 1.0000x reference)
.LBB0_120:
	s_and_b32 s6, s21, 7
	s_lshl_b32 s6, s6, 8
	s_waitcnt vmcnt(0)
	s_add_i32 s10, s20, 1
	s_or_b32 s6, s8, s6
	s_add_u32 s6, s92, s6
	v_mov_b32_e32 v0, 0
	s_addc_u32 s7, s93, s9
	s_mov_b32 s11, 0
	v_mov_b32_e32 v1, v0
	v_mov_b32_e32 v2, v0
	v_mov_b32_e32 v3, v0
	v_mov_b32_e32 v4, v0
	v_mov_b32_e32 v5, v0
	v_mov_b32_e32 v6, v0
	v_mov_b32_e32 v7, v0
	v_mov_b32_e32 v8, v0
	v_mov_b32_e32 v9, v0
	v_mov_b32_e32 v10, v0
	v_mov_b32_e32 v11, v0
	v_mov_b32_e32 v12, v0
	v_mov_b32_e32 v13, v0
	v_mov_b32_e32 v14, v0
	v_mov_b32_e32 v15, v0
	v_mov_b32_e32 v16, v0
	v_mov_b32_e32 v17, v0
	v_mov_b32_e32 v18, v0
	v_mov_b32_e32 v19, v0
	v_mov_b32_e32 v20, v0
	v_mov_b32_e32 v21, v0
	v_mov_b32_e32 v22, v0
	v_mov_b32_e32 v23, v0
	v_mov_b32_e32 v24, v0
	v_mov_b32_e32 v25, v0
	v_mov_b32_e32 v26, v0
	v_mov_b32_e32 v27, v0
	v_mov_b32_e32 v28, v0
	v_mov_b32_e32 v29, v0
	v_mov_b32_e32 v30, v0
	v_mov_b32_e32 v31, v0
	v_mov_b32_e32 v32, v0
	v_mov_b32_e32 v33, v0
	v_mov_b32_e32 v34, v0
	v_mov_b32_e32 v35, v0
	v_mov_b32_e32 v36, v0
	v_mov_b32_e32 v37, v0
	v_mov_b32_e32 v38, v0
	v_mov_b32_e32 v39, v0
	v_mov_b32_e32 v40, v0
	v_mov_b32_e32 v41, v0
	v_mov_b32_e32 v42, v0
	v_mov_b32_e32 v43, v0
	v_mov_b32_e32 v44, v0
	v_mov_b32_e32 v45, v0
	v_mov_b32_e32 v46, v0
	v_mov_b32_e32 v47, v0
	v_mov_b32_e32 v48, v0
	v_mov_b32_e32 v49, v0
	v_mov_b32_e32 v50, v0
	v_mov_b32_e32 v51, v0
	v_mov_b32_e32 v52, v0
	v_mov_b32_e32 v53, v0
	v_mov_b32_e32 v54, v0
	v_mov_b32_e32 v55, v0
	v_mov_b32_e32 v56, v0
	v_mov_b32_e32 v57, v0
	v_mov_b32_e32 v58, v0
	v_mov_b32_e32 v59, v0
	v_mov_b32_e32 v60, v0
	v_mov_b32_e32 v61, v0
	v_mov_b32_e32 v62, v0
	v_mov_b32_e32 v63, v0
	v_mov_b32_e32 v64, v0
	v_mov_b32_e32 v65, v0
	v_mov_b32_e32 v66, v0
	v_mov_b32_e32 v67, v0
	v_mov_b32_e32 v68, v0
	v_mov_b32_e32 v69, v0
	v_mov_b32_e32 v70, v0
	v_mov_b32_e32 v71, v0
	v_mov_b32_e32 v72, v0
	v_mov_b32_e32 v73, v0
	v_mov_b32_e32 v74, v0
	v_mov_b32_e32 v75, v0
	v_mov_b32_e32 v76, v0
	v_mov_b32_e32 v77, v0
	v_mov_b32_e32 v78, v0
	v_mov_b32_e32 v79, v0
	v_mov_b32_e32 v80, v0
	v_mov_b32_e32 v81, v0
	v_mov_b32_e32 v82, v0
	v_mov_b32_e32 v83, v0
	v_mov_b32_e32 v84, v0
	v_mov_b32_e32 v85, v0
	v_mov_b32_e32 v86, v0
	v_mov_b32_e32 v87, v0
	v_mov_b32_e32 v88, v0
	v_mov_b32_e32 v89, v0
	v_mov_b32_e32 v90, v0
	v_mov_b32_e32 v91, v0
	v_mov_b32_e32 v92, v0
	v_mov_b32_e32 v93, v0
	v_mov_b32_e32 v94, v0
	v_mov_b32_e32 v95, v0
	v_mov_b32_e32 v96, v0
	v_mov_b32_e32 v97, v0
	v_mov_b32_e32 v98, v0
	v_mov_b32_e32 v99, v0
	v_mov_b32_e32 v100, v0
	v_mov_b32_e32 v101, v0
	v_mov_b32_e32 v102, v0
	v_mov_b32_e32 v103, v0
	v_mov_b32_e32 v104, v0
	v_mov_b32_e32 v105, v0
	v_mov_b32_e32 v106, v0
	v_mov_b32_e32 v107, v0
	v_mov_b32_e32 v108, v0
	v_mov_b32_e32 v109, v0
	v_mov_b32_e32 v110, v0
	v_mov_b32_e32 v111, v0
	v_mov_b32_e32 v112, v0
	v_mov_b32_e32 v113, v0
	v_mov_b32_e32 v114, v0
	v_mov_b32_e32 v115, v0
	v_mov_b32_e32 v116, v0
	v_mov_b32_e32 v117, v0
	v_mov_b32_e32 v118, v0
	v_mov_b32_e32 v119, v0
	v_mov_b32_e32 v120, v0
	v_mov_b32_e32 v121, v0
	v_mov_b32_e32 v122, v0
	v_mov_b32_e32 v123, v0
	v_mov_b32_e32 v124, v0
	v_mov_b32_e32 v125, v0
	v_mov_b32_e32 v126, v0
	v_mov_b32_e32 v127, v0
	v_mov_b32_e32 v174, v0
	v_mov_b32_e32 v175, v0
	s_waitcnt lgkmcnt(0)
	s_barrier
	v_mov_b32_e32 v128, v218
	v_and_b32_e32 v129, 31, v128
	v_bfe_u32 v130, v128, 5, 1
	v_bfe_u32 v131, v128, 2, 2
	v_and_b32_e32 v132, 16, v128
	v_lshlrev_b32_e32 v128, 2, v128
	v_mul_u32_u24_e32 v136, 0x110, v129
	v_lshlrev_b32_e32 v137, 4, v130
	v_and_or_b32 v128, v128, 12, v132
	v_lshl_or_b32 v129, v130, 2, v131
	v_add3_u32 v165, s28, v136, v137
	v_mul_u32_u24_e32 v162, 0x140, v129
	v_lshlrev_b32_e32 v134, 1, v128
	v_add_u32_e32 v163, v162, v134
	v_mov_b32_e32 v170, 0
	v_mov_b32_e32 v171, 0
	v_mov_b32_e32 v172, 0
	v_mov_b32_e32 v173, 0
	s_branch .LBB0_122
.LBB0_121:
	s_mul_i32 s8, s20, 0x4400
	s_mul_i32 s9, s20, 0x5000
	s_sub_i32 s8, s8, s28
	s_add_i32 s11, s11, 1
	v_add_u32_e32 v164, s8, v165
	v_add_u32_e32 v162, s9, v163
	ds_read_b128 v[128:131], v164
	ds_read_b128 v[132:135], v164 offset:8704
	ds_read_b128 v[136:139], v165
	ds_read_b128 v[176:179], v164 offset:32
	ds_read_b128 v[180:183], v164 offset:8736
	ds_read_b128 v[184:187], v165 offset:32
	s_waitcnt lgkmcnt(3)
	s_setprio 1
	v_mfma_f32_32x32x16_bf16 v[144:159], v[128:131], v[136:139], 0
	v_mfma_f32_32x32x16_bf16 v[128:143], v[132:135], v[136:139], 0
	s_setprio 0
	ds_read_b128 v[188:191], v164 offset:64
	ds_read_b128 v[192:195], v164 offset:8768
	ds_read_b128 v[196:199], v165 offset:64
	s_waitcnt lgkmcnt(3)
	s_setprio 1
	v_mfma_f32_32x32x16_bf16 v[144:159], v[176:179], v[184:187], v[144:159]
	v_mfma_f32_32x32x16_bf16 v[128:143], v[180:183], v[184:187], v[128:143]
	s_setprio 0
	ds_read_b128 v[200:203], v164 offset:96
	ds_read_b128 v[204:207], v164 offset:8800
	ds_read_b128 v[208:211], v165 offset:96
	s_waitcnt lgkmcnt(3)
	s_setprio 1
	v_mfma_f32_32x32x16_bf16 v[144:159], v[188:191], v[196:199], v[144:159]
	v_mfma_f32_32x32x16_bf16 v[128:143], v[192:195], v[196:199], v[128:143]
	s_setprio 0
	s_waitcnt lgkmcnt(0)
	s_setprio 1
	v_mfma_f32_32x32x16_bf16 v[144:159], v[200:203], v[208:211], v[144:159]
	v_mfma_f32_32x32x16_bf16 v[128:143], v[204:207], v[208:211], v[128:143]
	s_setprio 0
	ds_read_b128 v[208:211], v164 offset:128
	ds_read_b128 v[212:215], v164 offset:8832
	ds_read_b128 v[250:253], v165 offset:128
	ds_read_b128 v[166:169], v164 offset:160
	ds_read_b128 v[232:235], v164 offset:8864
	ds_read_b128 v[246:249], v165 offset:160
	ds_read_b64_tr_b16 v[224:225], v162 offset:34816
	ds_read_b64_tr_b16 v[226:227], v162 offset:37376
	ds_read_b64_tr_b16 v[228:229], v162 offset:34880
	ds_read_b64_tr_b16 v[230:231], v162 offset:37440
	s_waitcnt lgkmcnt(7)
	s_setprio 1
	v_mfma_f32_32x32x16_bf16 v[176:191], v[208:211], v[250:253], 0
	v_mfma_f32_32x32x16_bf16 v[192:207], v[212:215], v[250:253], 0
	s_setprio 0
	ds_read_b128 v[208:211], v164 offset:192
	ds_read_b128 v[212:215], v164 offset:8896
	ds_read_b128 v[250:253], v165 offset:192
	v_exp_f32_e32 v144, v144
	v_exp_f32_e32 v145, v145
	s_nop 0
	v_pk_add_f32 v[170:171], v[170:171], v[144:145]
	v_cvt_pk_bf16_f32 v144, v144, v145
	s_waitcnt lgkmcnt(7)
	s_setprio 1
	v_mfma_f32_32x32x16_bf16 v[176:191], v[166:169], v[246:249], v[176:191]
	v_mfma_f32_32x32x16_bf16 v[192:207], v[232:235], v[246:249], v[192:207]
	s_setprio 0
	ds_read_b128 v[166:169], v164 offset:224
	ds_read_b128 v[232:235], v164 offset:8928
	ds_read_b128 v[246:249], v165 offset:224
	v_exp_f32_e32 v146, v146
	v_exp_f32_e32 v147, v147
	s_nop 0
	v_pk_add_f32 v[170:171], v[170:171], v[146:147]
	v_cvt_pk_bf16_f32 v145, v146, v147
	s_waitcnt lgkmcnt(3)
	s_setprio 1
	v_mfma_f32_32x32x16_bf16 v[176:191], v[208:211], v[250:253], v[176:191]
	v_mfma_f32_32x32x16_bf16 v[192:207], v[212:215], v[250:253], v[192:207]
	s_setprio 0
	v_exp_f32_e32 v148, v148
	v_exp_f32_e32 v149, v149
	s_nop 0
	v_pk_add_f32 v[170:171], v[170:171], v[148:149]
	v_cvt_pk_bf16_f32 v146, v148, v149
	s_waitcnt lgkmcnt(0)
	s_setprio 1
	v_mfma_f32_32x32x16_bf16 v[176:191], v[166:169], v[246:249], v[176:191]
	v_mfma_f32_32x32x16_bf16 v[192:207], v[232:235], v[246:249], v[192:207]
	s_setprio 0
	ds_read_b64_tr_b16 v[232:233], v162 offset:34944
	ds_read_b64_tr_b16 v[234:235], v162 offset:37504
	ds_read_b64_tr_b16 v[246:247], v162 offset:35008
	ds_read_b64_tr_b16 v[248:249], v162 offset:37568
	v_exp_f32_e32 v150, v150
	v_exp_f32_e32 v151, v151
	s_nop 0
	v_pk_add_f32 v[170:171], v[170:171], v[150:151]
	v_cvt_pk_bf16_f32 v147, v150, v151
	s_waitcnt lgkmcnt(0)
	s_setprio 1
	v_mfma_f32_32x32x16_bf16 v[112:127], v[144:147], v[224:227], v[112:127]
	v_exp_f32_e32 v176, v176
	v_exp_f32_e32 v177, v177
	ds_read_b64_tr_b16 v[208:209], v162 offset:39936
	ds_read_b64_tr_b16 v[210:211], v162 offset:42496
	v_pk_add_f32 v[172:173], v[172:173], v[176:177]
	v_cvt_pk_bf16_f32 v176, v176, v177
	v_mfma_f32_32x32x16_bf16 v[96:111], v[144:147], v[228:231], v[96:111]
	v_exp_f32_e32 v178, v178
	v_exp_f32_e32 v179, v179
	s_nop 0
	v_pk_add_f32 v[172:173], v[172:173], v[178:179]
	v_cvt_pk_bf16_f32 v177, v178, v179
	v_mfma_f32_32x32x16_bf16 v[80:95], v[144:147], v[232:235], v[80:95]
	v_exp_f32_e32 v180, v180
	v_exp_f32_e32 v181, v181
	ds_read_b64_tr_b16 v[212:213], v162 offset:40000
	ds_read_b64_tr_b16 v[214:215], v162 offset:42560
	v_pk_add_f32 v[172:173], v[172:173], v[180:181]
	v_cvt_pk_bf16_f32 v178, v180, v181
	v_mfma_f32_32x32x16_bf16 v[64:79], v[144:147], v[246:249], v[64:79]
	v_exp_f32_e32 v182, v182
	v_exp_f32_e32 v183, v183
	s_nop 0
	v_pk_add_f32 v[172:173], v[172:173], v[182:183]
	v_cvt_pk_bf16_f32 v179, v182, v183
	s_setprio 0
	s_waitcnt lgkmcnt(4)
	s_setprio 1
	v_mfma_f32_32x32x16_bf16 v[48:63], v[176:179], v[224:227], v[48:63]
	v_exp_f32_e32 v152, v152
	v_exp_f32_e32 v153, v153
	ds_read_b64_tr_b16 v[250:251], v162 offset:40064
	ds_read_b64_tr_b16 v[252:253], v162 offset:42624
	v_pk_add_f32 v[170:171], v[170:171], v[152:153]
	v_cvt_pk_bf16_f32 v152, v152, v153
	v_mfma_f32_32x32x16_bf16 v[32:47], v[176:179], v[228:231], v[32:47]
	v_exp_f32_e32 v154, v154
	v_exp_f32_e32 v155, v155
	s_nop 0
	v_pk_add_f32 v[170:171], v[170:171], v[154:155]
	v_cvt_pk_bf16_f32 v153, v154, v155
	v_mfma_f32_32x32x16_bf16 v[16:31], v[176:179], v[232:235], v[16:31]
	v_exp_f32_e32 v156, v156
	v_exp_f32_e32 v157, v157
	ds_read_b64_tr_b16 v[166:167], v162 offset:40128
	ds_read_b64_tr_b16 v[168:169], v162 offset:42688
	v_pk_add_f32 v[170:171], v[170:171], v[156:157]
	v_cvt_pk_bf16_f32 v154, v156, v157
	v_mfma_f32_32x32x16_bf16 v[0:15], v[176:179], v[246:249], v[0:15]
	v_exp_f32_e32 v158, v158
	v_exp_f32_e32 v159, v159
	s_nop 0
	v_pk_add_f32 v[170:171], v[170:171], v[158:159]
	v_cvt_pk_bf16_f32 v155, v158, v159
	s_setprio 0
	s_waitcnt lgkmcnt(0)
	s_setprio 1
	v_mfma_f32_32x32x16_bf16 v[112:127], v[152:155], v[208:211], v[112:127]
	v_exp_f32_e32 v184, v184
	v_exp_f32_e32 v185, v185
	ds_read_b64_tr_b16 v[224:225], v162 offset:45056
	ds_read_b64_tr_b16 v[226:227], v162 offset:47616
	v_pk_add_f32 v[172:173], v[172:173], v[184:185]
	v_cvt_pk_bf16_f32 v184, v184, v185
	v_mfma_f32_32x32x16_bf16 v[96:111], v[152:155], v[212:215], v[96:111]
	v_exp_f32_e32 v186, v186
	v_exp_f32_e32 v187, v187
	s_nop 0
	v_pk_add_f32 v[172:173], v[172:173], v[186:187]
	v_cvt_pk_bf16_f32 v185, v186, v187
	v_mfma_f32_32x32x16_bf16 v[80:95], v[152:155], v[250:253], v[80:95]
	v_exp_f32_e32 v188, v188
	v_exp_f32_e32 v189, v189
	ds_read_b64_tr_b16 v[228:229], v162 offset:45120
	ds_read_b64_tr_b16 v[230:231], v162 offset:47680
	v_pk_add_f32 v[172:173], v[172:173], v[188:189]
	v_cvt_pk_bf16_f32 v186, v188, v189
	v_mfma_f32_32x32x16_bf16 v[64:79], v[152:155], v[166:169], v[64:79]
	v_exp_f32_e32 v190, v190
	v_exp_f32_e32 v191, v191
	s_nop 0
	v_pk_add_f32 v[172:173], v[172:173], v[190:191]
	v_cvt_pk_bf16_f32 v187, v190, v191
	s_setprio 0
	s_waitcnt lgkmcnt(4)
	s_setprio 1
	v_mfma_f32_32x32x16_bf16 v[48:63], v[184:187], v[208:211], v[48:63]
	v_exp_f32_e32 v128, v128
	v_exp_f32_e32 v129, v129
	ds_read_b64_tr_b16 v[232:233], v162 offset:45184
	ds_read_b64_tr_b16 v[234:235], v162 offset:47744
	v_pk_add_f32 v[170:171], v[170:171], v[128:129]
	v_cvt_pk_bf16_f32 v128, v128, v129
	v_mfma_f32_32x32x16_bf16 v[32:47], v[184:187], v[212:215], v[32:47]
	v_exp_f32_e32 v130, v130
	v_exp_f32_e32 v131, v131
	s_nop 0
	v_pk_add_f32 v[170:171], v[170:171], v[130:131]
	v_cvt_pk_bf16_f32 v129, v130, v131
	v_mfma_f32_32x32x16_bf16 v[16:31], v[184:187], v[250:253], v[16:31]
	v_exp_f32_e32 v132, v132
	v_exp_f32_e32 v133, v133
	ds_read_b64_tr_b16 v[246:247], v162 offset:45248
	ds_read_b64_tr_b16 v[248:249], v162 offset:47808
	v_pk_add_f32 v[170:171], v[170:171], v[132:133]
	v_cvt_pk_bf16_f32 v130, v132, v133
	v_mfma_f32_32x32x16_bf16 v[0:15], v[184:187], v[166:169], v[0:15]
	v_exp_f32_e32 v134, v134
	v_exp_f32_e32 v135, v135
	s_nop 0
	v_pk_add_f32 v[170:171], v[170:171], v[134:135]
	v_cvt_pk_bf16_f32 v131, v134, v135
	s_setprio 0
	s_waitcnt lgkmcnt(0)
	s_setprio 1
	v_mfma_f32_32x32x16_bf16 v[112:127], v[128:131], v[224:227], v[112:127]
	v_exp_f32_e32 v192, v192
	v_exp_f32_e32 v193, v193
	ds_read_b64_tr_b16 v[208:209], v162 offset:50176
	ds_read_b64_tr_b16 v[210:211], v162 offset:52736
	v_pk_add_f32 v[172:173], v[172:173], v[192:193]
	v_cvt_pk_bf16_f32 v192, v192, v193
	v_mfma_f32_32x32x16_bf16 v[96:111], v[128:131], v[228:231], v[96:111]
	v_exp_f32_e32 v194, v194
	v_exp_f32_e32 v195, v195
	s_nop 0
	v_pk_add_f32 v[172:173], v[172:173], v[194:195]
	v_cvt_pk_bf16_f32 v193, v194, v195
	v_mfma_f32_32x32x16_bf16 v[80:95], v[128:131], v[232:235], v[80:95]
	v_exp_f32_e32 v196, v196
	v_exp_f32_e32 v197, v197
	ds_read_b64_tr_b16 v[212:213], v162 offset:50240
	ds_read_b64_tr_b16 v[214:215], v162 offset:52800
	v_pk_add_f32 v[172:173], v[172:173], v[196:197]
	v_cvt_pk_bf16_f32 v194, v196, v197
	v_mfma_f32_32x32x16_bf16 v[64:79], v[128:131], v[246:249], v[64:79]
	v_exp_f32_e32 v198, v198
	v_exp_f32_e32 v199, v199
	s_nop 0
	v_pk_add_f32 v[172:173], v[172:173], v[198:199]
	v_cvt_pk_bf16_f32 v195, v198, v199
	s_setprio 0
	s_waitcnt lgkmcnt(4)
	s_setprio 1
	v_mfma_f32_32x32x16_bf16 v[48:63], v[192:195], v[224:227], v[48:63]
	v_exp_f32_e32 v136, v136
	v_exp_f32_e32 v137, v137
	ds_read_b64_tr_b16 v[250:251], v162 offset:50304
	ds_read_b64_tr_b16 v[252:253], v162 offset:52864
	v_pk_add_f32 v[170:171], v[170:171], v[136:137]
	v_cvt_pk_bf16_f32 v136, v136, v137
	v_mfma_f32_32x32x16_bf16 v[32:47], v[192:195], v[228:231], v[32:47]
	v_exp_f32_e32 v138, v138
	v_exp_f32_e32 v139, v139
	s_nop 0
	v_pk_add_f32 v[170:171], v[170:171], v[138:139]
	v_cvt_pk_bf16_f32 v137, v138, v139
	v_mfma_f32_32x32x16_bf16 v[16:31], v[192:195], v[232:235], v[16:31]
	v_exp_f32_e32 v140, v140
	v_exp_f32_e32 v141, v141
	ds_read_b64_tr_b16 v[166:167], v162 offset:50368
	ds_read_b64_tr_b16 v[168:169], v162 offset:52928
	v_pk_add_f32 v[170:171], v[170:171], v[140:141]
	v_cvt_pk_bf16_f32 v138, v140, v141
	v_mfma_f32_32x32x16_bf16 v[0:15], v[192:195], v[246:249], v[0:15]
	v_exp_f32_e32 v142, v142
	v_exp_f32_e32 v143, v143
	s_nop 0
	v_pk_add_f32 v[170:171], v[170:171], v[142:143]
	v_cvt_pk_bf16_f32 v139, v142, v143
	s_setprio 0
	s_waitcnt lgkmcnt(0)
	s_setprio 1
	v_mfma_f32_32x32x16_bf16 v[112:127], v[136:139], v[208:211], v[112:127]
	v_exp_f32_e32 v200, v200
	v_exp_f32_e32 v201, v201
	s_nop 0
	v_pk_add_f32 v[172:173], v[172:173], v[200:201]
	v_cvt_pk_bf16_f32 v200, v200, v201
	v_mfma_f32_32x32x16_bf16 v[96:111], v[136:139], v[212:215], v[96:111]
	v_exp_f32_e32 v202, v202
	v_exp_f32_e32 v203, v203
	s_nop 0
	v_pk_add_f32 v[172:173], v[172:173], v[202:203]
	v_cvt_pk_bf16_f32 v201, v202, v203
	v_mfma_f32_32x32x16_bf16 v[80:95], v[136:139], v[250:253], v[80:95]
	v_exp_f32_e32 v204, v204
	v_exp_f32_e32 v205, v205
	s_nop 0
	v_pk_add_f32 v[172:173], v[172:173], v[204:205]
	v_cvt_pk_bf16_f32 v202, v204, v205
	v_mfma_f32_32x32x16_bf16 v[64:79], v[136:139], v[166:169], v[64:79]
	v_exp_f32_e32 v206, v206
	v_exp_f32_e32 v207, v207
	s_nop 0
	v_pk_add_f32 v[172:173], v[172:173], v[206:207]
	v_cvt_pk_bf16_f32 v203, v206, v207
	s_setprio 0
	s_waitcnt lgkmcnt(0)
	s_setprio 1
	v_mfma_f32_32x32x16_bf16 v[48:63], v[200:203], v[208:211], v[48:63]
	v_mfma_f32_32x32x16_bf16 v[32:47], v[200:203], v[212:215], v[32:47]
	v_mfma_f32_32x32x16_bf16 v[16:31], v[200:203], v[250:253], v[16:31]
	v_mfma_f32_32x32x16_bf16 v[0:15], v[200:203], v[166:169], v[0:15]
	s_setprio 0
	s_waitcnt vmcnt(0)
	s_add_u32 s6, s6, 0x20000
	s_addc_u32 s7, s7, 0
	s_cmp_eq_u32 s10, s11
	s_barrier
	s_cbranch_scc1 .LBB0_126

.LBB0_126:
	v_add_f32_e32 v174, v170, v171
	v_add_f32_e32 v175, v172, v173
	v_mov_b32_e32 v128, v218
	s_and_b32 s6, s10, 1
	s_mul_i32 s7, s6, 0x4400
	v_and_b32_e32 v129, 31, v128
	v_bfe_u32 v130, v128, 5, 1
	v_bfe_u32 v131, v128, 2, 2
	v_and_b32_e32 v132, 16, v128
	v_lshlrev_b32_e32 v128, 2, v128
	v_and_or_b32 v128, v128, 12, v132
	s_add_i32 s7, s7, 0
	v_mul_u32_u24_e32 v129, 0x110, v129
	v_lshlrev_b32_e32 v132, 4, v130
	s_mulk_i32 s6, 0xc00
	v_lshl_or_b32 v130, v130, 2, v131
	v_add3_u32 v162, s7, v129, v132
	s_add_i32 s7, s7, s6
	v_mul_u32_u24_e32 v130, 0x140, v130
	v_lshlrev_b32_e32 v128, 1, v128
	v_add3_u32 v160, s7, v130, v128
	v_add3_u32 v163, s28, v129, v132
	ds_read_b128 v[128:131], v162
	ds_read_b128 v[132:135], v162 offset:8704
	ds_read_b128 v[136:139], v163
	ds_read_b128 v[176:179], v162 offset:32
	ds_read_b128 v[180:183], v162 offset:8736
	ds_read_b128 v[184:187], v163 offset:32
	s_setprio 1
	s_waitcnt lgkmcnt(3)
	v_mfma_f32_32x32x16_bf16 v[144:159], v[128:131], v[136:139], 0
	v_mfma_f32_32x32x16_bf16 v[128:143], v[132:135], v[136:139], 0
	s_setprio 0
	ds_read_b128 v[188:191], v162 offset:64
	ds_read_b128 v[192:195], v162 offset:8768
	ds_read_b128 v[196:199], v163 offset:64
	s_setprio 1
	s_waitcnt lgkmcnt(3)
	v_mfma_f32_32x32x16_bf16 v[128:143], v[180:183], v[184:187], v[128:143]
	v_mfma_f32_32x32x16_bf16 v[144:159], v[176:179], v[184:187], v[144:159]
	s_setprio 0
	ds_read_b128 v[176:179], v162 offset:96
	ds_read_b128 v[180:183], v162 offset:8800
	ds_read_b128 v[184:187], v163 offset:96
	s_setprio 1
	s_waitcnt lgkmcnt(3)
	v_mfma_f32_32x32x16_bf16 v[128:143], v[192:195], v[196:199], v[128:143]
	v_mfma_f32_32x32x16_bf16 v[144:159], v[188:191], v[196:199], v[144:159]
	s_setprio 0
	s_setprio 1
	s_waitcnt lgkmcnt(0)
	v_mfma_f32_32x32x16_bf16 v[128:143], v[180:183], v[184:187], v[128:143]
	v_mfma_f32_32x32x16_bf16 v[144:159], v[176:179], v[184:187], v[144:159]
	s_setprio 0
	ds_read_b64_tr_b16 v[176:177], v160 offset:34816
	ds_read_b64_tr_b16 v[180:181], v160 offset:34880
	ds_read_b64_tr_b16 v[184:185], v160 offset:34944
	ds_read_b64_tr_b16 v[188:189], v160 offset:35008
	ds_read_b64_tr_b16 v[178:179], v160 offset:37376
	ds_read_b64_tr_b16 v[182:183], v160 offset:37440
	ds_read_b64_tr_b16 v[186:187], v160 offset:37504
	ds_read_b64_tr_b16 v[190:191], v160 offset:37568
	s_nop 2
	v_exp_f32_e32 v144, v144
	v_exp_f32_e32 v145, v145
	v_exp_f32_e32 v146, v146
	v_exp_f32_e32 v147, v147
	v_exp_f32_e32 v148, v148
	v_exp_f32_e32 v149, v149
	v_exp_f32_e32 v150, v150
	v_exp_f32_e32 v151, v151
	v_add_f32_e32 v164, v144, v145
	v_cvt_pk_bf16_f32 v144, v144, v145
	v_add_f32_e32 v165, v146, v147
	v_cvt_pk_bf16_f32 v145, v146, v147
	v_add_f32_e32 v166, v148, v149
	v_cvt_pk_bf16_f32 v146, v148, v149
	v_add_f32_e32 v167, v150, v151
	v_cvt_pk_bf16_f32 v147, v150, v151
	s_setprio 1
	s_waitcnt lgkmcnt(3)
	v_mfma_f32_32x32x16_bf16 v[112:127], v[144:147], v[176:179], v[112:127]
	ds_read_b64_tr_b16 v[148:149], v160 offset:39936
	ds_read_b64_tr_b16 v[150:151], v160 offset:42496
	ds_read_b64_tr_b16 v[176:177], v160 offset:40000
	ds_read_b64_tr_b16 v[178:179], v160 offset:42560
	v_exp_f32_e32 v152, v152
	v_exp_f32_e32 v153, v153
	s_nop 0
	v_add_f32_e32 v168, v152, v153
	v_cvt_pk_bf16_f32 v152, v152, v153
	s_waitcnt lgkmcnt(6)
	v_mfma_f32_32x32x16_bf16 v[96:111], v[144:147], v[180:183], v[96:111]
	v_exp_f32_e32 v153, v154
	v_exp_f32_e32 v154, v155
	s_nop 0
	v_add_f32_e32 v169, v153, v154
	v_cvt_pk_bf16_f32 v153, v153, v154
	s_waitcnt lgkmcnt(5)
	v_mfma_f32_32x32x16_bf16 v[80:95], v[144:147], v[184:187], v[80:95]
	ds_read_b64_tr_b16 v[180:181], v160 offset:40064
	ds_read_b64_tr_b16 v[182:183], v160 offset:42624
	ds_read_b64_tr_b16 v[184:185], v160 offset:40128
	ds_read_b64_tr_b16 v[186:187], v160 offset:42688
	v_exp_f32_e32 v154, v156
	v_exp_f32_e32 v155, v157
	s_nop 0
	v_add_f32_e32 v170, v154, v155
	v_cvt_pk_bf16_f32 v154, v154, v155
	s_waitcnt lgkmcnt(8)
	v_mfma_f32_32x32x16_bf16 v[64:79], v[144:147], v[188:191], v[64:79]
	v_exp_f32_e32 v144, v158
	v_exp_f32_e32 v145, v159
	s_nop 0
	v_add_f32_e32 v171, v144, v145
	v_cvt_pk_bf16_f32 v155, v144, v145
	s_setprio 0
	s_setprio 1
	s_waitcnt lgkmcnt(6)
	v_mfma_f32_32x32x16_bf16 v[112:127], v[152:155], v[148:151], v[112:127]
	ds_read_b64_tr_b16 v[144:145], v160 offset:45056
	ds_read_b64_tr_b16 v[146:147], v160 offset:47616
	ds_read_b64_tr_b16 v[148:149], v160 offset:45120
	ds_read_b64_tr_b16 v[150:151], v160 offset:47680
	v_exp_f32_e32 v128, v128
	v_exp_f32_e32 v129, v129
	s_nop 0
	v_add_f32_e32 v172, v128, v129
	v_cvt_pk_bf16_f32 v128, v128, v129
	s_waitcnt lgkmcnt(8)
	v_mfma_f32_32x32x16_bf16 v[96:111], v[152:155], v[176:179], v[96:111]
	v_exp_f32_e32 v129, v130
	v_exp_f32_e32 v130, v131
	s_nop 0
	v_add_f32_e32 v173, v129, v130
	v_cvt_pk_bf16_f32 v129, v129, v130
	s_waitcnt lgkmcnt(6)
	v_mfma_f32_32x32x16_bf16 v[80:95], v[152:155], v[180:183], v[80:95]
	ds_read_b64_tr_b16 v[156:157], v160 offset:45184
	ds_read_b64_tr_b16 v[158:159], v160 offset:47744
	ds_read_b64_tr_b16 v[180:181], v160 offset:45248
	ds_read_b64_tr_b16 v[182:183], v160 offset:47808
	v_exp_f32_e32 v130, v132
	v_exp_f32_e32 v131, v133
	s_nop 0
	v_add_f32_e32 v188, v130, v131
	v_cvt_pk_bf16_f32 v130, v130, v131
	s_waitcnt lgkmcnt(8)
	v_mfma_f32_32x32x16_bf16 v[64:79], v[152:155], v[184:187], v[64:79]
	v_exp_f32_e32 v131, v134
	v_exp_f32_e32 v132, v135
	s_nop 0
	v_add_f32_e32 v152, v131, v132
	v_cvt_pk_bf16_f32 v131, v131, v132
	s_setprio 0
	s_setprio 1
	s_waitcnt lgkmcnt(6)
	v_mfma_f32_32x32x16_bf16 v[112:127], v[128:131], v[144:147], v[112:127]
	v_exp_f32_e32 v132, v136
	v_exp_f32_e32 v133, v137
	s_nop 0
	v_add_f32_e32 v176, v132, v133
	v_cvt_pk_bf16_f32 v184, v132, v133
	s_waitcnt lgkmcnt(4)
	v_mfma_f32_32x32x16_bf16 v[96:111], v[128:131], v[148:151], v[96:111]
	v_exp_f32_e32 v132, v138
	v_exp_f32_e32 v133, v139
	s_nop 0
	v_add_f32_e32 v177, v132, v133
	v_cvt_pk_bf16_f32 v185, v132, v133
	s_waitcnt lgkmcnt(2)
	v_mfma_f32_32x32x16_bf16 v[80:95], v[128:131], v[156:159], v[80:95]
	v_exp_f32_e32 v132, v140
	v_exp_f32_e32 v133, v141
	s_nop 0
	v_add_f32_e32 v178, v132, v133
	v_cvt_pk_bf16_f32 v186, v132, v133
	s_waitcnt lgkmcnt(0)
	v_mfma_f32_32x32x16_bf16 v[64:79], v[128:131], v[180:183], v[64:79]
	v_exp_f32_e32 v128, v142
	v_exp_f32_e32 v129, v143
	s_nop 0
	v_add_f32_e32 v179, v128, v129
	v_cvt_pk_bf16_f32 v187, v128, v129
	s_setprio 0
	ds_read_b128 v[128:131], v162 offset:128
	ds_read_b128 v[132:135], v162 offset:8832
	ds_read_b128 v[136:139], v163 offset:128
	v_add_f32_e32 v140, v174, v164
	v_add_f32_e32 v140, v165, v140
	v_add_f32_e32 v140, v166, v140
	v_add_f32_e32 v140, v167, v140
	v_add_f32_e32 v140, v168, v140
	v_add_f32_e32 v140, v169, v140
	v_add_f32_e32 v140, v170, v140
	v_add_f32_e32 v140, v171, v140
	v_add_f32_e32 v140, v172, v140
	v_add_f32_e32 v140, v173, v140
	v_add_f32_e32 v140, v188, v140
	ds_read_b128 v[180:183], v162 offset:160
	ds_read_b128 v[188:191], v162 offset:8864
	ds_read_b128 v[192:195], v163 offset:160
	v_add_f32_e32 v174, v152, v140
	s_setprio 1
	s_waitcnt lgkmcnt(3)
	v_mfma_f32_32x32x16_bf16 v[144:159], v[128:131], v[136:139], 0
	v_mfma_f32_32x32x16_bf16 v[128:143], v[132:135], v[136:139], 0
	s_setprio 0
	ds_read_b128 v[196:199], v162 offset:192
	ds_read_b128 v[200:203], v162 offset:8896
	ds_read_b128 v[204:207], v163 offset:192
	s_setprio 1
	s_waitcnt lgkmcnt(3)
	v_mfma_f32_32x32x16_bf16 v[128:143], v[188:191], v[192:195], v[128:143]
	v_mfma_f32_32x32x16_bf16 v[144:159], v[180:183], v[192:195], v[144:159]
	s_setprio 0
	ds_read_b128 v[180:183], v162 offset:224
	ds_read_b128 v[188:191], v162 offset:8928
	ds_read_b128 v[192:195], v163 offset:224
	s_setprio 1
	s_waitcnt lgkmcnt(3)
	v_mfma_f32_32x32x16_bf16 v[128:143], v[200:203], v[204:207], v[128:143]
	v_mfma_f32_32x32x16_bf16 v[144:159], v[196:199], v[204:207], v[144:159]
	s_setprio 0
	ds_read_b64_tr_b16 v[196:197], v160 offset:50176
	ds_read_b64_tr_b16 v[200:201], v160 offset:50240
	ds_read_b64_tr_b16 v[204:205], v160 offset:50304
	ds_read_b64_tr_b16 v[208:209], v160 offset:50368
	ds_read_b64_tr_b16 v[198:199], v160 offset:52736
	ds_read_b64_tr_b16 v[202:203], v160 offset:52800
	ds_read_b64_tr_b16 v[206:207], v160 offset:52864
	ds_read_b64_tr_b16 v[210:211], v160 offset:52928
	s_setprio 1
	s_waitcnt lgkmcnt(8)
	v_mfma_f32_32x32x16_bf16 v[128:143], v[188:191], v[192:195], v[128:143]
	v_mfma_f32_32x32x16_bf16 v[144:159], v[180:183], v[192:195], v[144:159]
	s_setprio 0
	s_setprio 1
	s_waitcnt lgkmcnt(3)
	v_mfma_f32_32x32x16_bf16 v[112:127], v[184:187], v[196:199], v[112:127]
	ds_read_b64_tr_b16 v[180:181], v160 offset:34816
	ds_read_b64_tr_b16 v[182:183], v160 offset:37376
	ds_read_b64_tr_b16 v[188:189], v160 offset:34880
	ds_read_b64_tr_b16 v[190:191], v160 offset:37440
	s_nop 3
	v_exp_f32_e32 v144, v144
	v_exp_f32_e32 v145, v145
	s_nop 0
	v_add_f32_e32 v162, v144, v145
	v_cvt_pk_bf16_f32 v144, v144, v145
	s_waitcnt lgkmcnt(6)
	v_mfma_f32_32x32x16_bf16 v[96:111], v[184:187], v[200:203], v[96:111]
	v_exp_f32_e32 v145, v146
	v_exp_f32_e32 v146, v147
	s_nop 0
	v_add_f32_e32 v163, v145, v146
	v_cvt_pk_bf16_f32 v145, v145, v146
	s_waitcnt lgkmcnt(5)
	v_mfma_f32_32x32x16_bf16 v[80:95], v[184:187], v[204:207], v[80:95]
	ds_read_b64_tr_b16 v[192:193], v160 offset:34944
	ds_read_b64_tr_b16 v[194:195], v160 offset:37504
	ds_read_b64_tr_b16 v[196:197], v160 offset:35008
	ds_read_b64_tr_b16 v[198:199], v160 offset:37568
	v_exp_f32_e32 v146, v148
	v_exp_f32_e32 v147, v149
	s_nop 0
	v_add_f32_e32 v164, v146, v147
	v_cvt_pk_bf16_f32 v146, v146, v147
	s_waitcnt lgkmcnt(8)
	v_mfma_f32_32x32x16_bf16 v[64:79], v[184:187], v[208:211], v[64:79]
	v_exp_f32_e32 v147, v150
	v_exp_f32_e32 v148, v151
	s_nop 0
	v_add_f32_e32 v165, v147, v148
	v_cvt_pk_bf16_f32 v147, v147, v148
	s_setprio 0
	s_setprio 1
	s_waitcnt lgkmcnt(6)
	v_mfma_f32_32x32x16_bf16 v[48:63], v[144:147], v[180:183], v[48:63]
	ds_read_b64_tr_b16 v[148:149], v160 offset:39936
	ds_read_b64_tr_b16 v[150:151], v160 offset:42496
	ds_read_b64_tr_b16 v[180:181], v160 offset:40000
	ds_read_b64_tr_b16 v[182:183], v160 offset:42560
	v_exp_f32_e32 v152, v152
	v_exp_f32_e32 v153, v153
	s_nop 0
	v_add_f32_e32 v166, v152, v153
	v_cvt_pk_bf16_f32 v152, v152, v153
	s_waitcnt lgkmcnt(8)
	v_mfma_f32_32x32x16_bf16 v[32:47], v[144:147], v[188:191], v[32:47]
	v_exp_f32_e32 v153, v154
	v_exp_f32_e32 v154, v155
	s_nop 0
	v_add_f32_e32 v167, v153, v154
	v_cvt_pk_bf16_f32 v153, v153, v154
	s_waitcnt lgkmcnt(6)
	v_mfma_f32_32x32x16_bf16 v[16:31], v[144:147], v[192:195], v[16:31]
	ds_read_b64_tr_b16 v[184:185], v160 offset:40064
	ds_read_b64_tr_b16 v[186:187], v160 offset:42624
	ds_read_b64_tr_b16 v[188:189], v160 offset:40128
	ds_read_b64_tr_b16 v[190:191], v160 offset:42688
	v_exp_f32_e32 v154, v156
	v_exp_f32_e32 v155, v157
	s_nop 0
	v_add_f32_e32 v168, v154, v155
	v_cvt_pk_bf16_f32 v154, v154, v155
	s_waitcnt lgkmcnt(8)
	v_mfma_f32_32x32x16_bf16 v[0:15], v[144:147], v[196:199], v[0:15]
	v_exp_f32_e32 v144, v158
	v_exp_f32_e32 v145, v159
	s_nop 0
	v_add_f32_e32 v169, v144, v145
	v_cvt_pk_bf16_f32 v155, v144, v145
	s_setprio 0
	s_setprio 1
	s_waitcnt lgkmcnt(6)
	v_mfma_f32_32x32x16_bf16 v[48:63], v[152:155], v[148:151], v[48:63]
	ds_read_b64_tr_b16 v[144:145], v160 offset:45056
	ds_read_b64_tr_b16 v[146:147], v160 offset:47616
	ds_read_b64_tr_b16 v[148:149], v160 offset:45120
	ds_read_b64_tr_b16 v[150:151], v160 offset:47680
	v_exp_f32_e32 v128, v128
	v_exp_f32_e32 v129, v129
	s_nop 0
	v_add_f32_e32 v170, v128, v129
	v_cvt_pk_bf16_f32 v128, v128, v129
	s_waitcnt lgkmcnt(8)
	v_mfma_f32_32x32x16_bf16 v[32:47], v[152:155], v[180:183], v[32:47]
	v_exp_f32_e32 v129, v130
	v_exp_f32_e32 v130, v131
	s_nop 0
	v_add_f32_e32 v171, v129, v130
	v_cvt_pk_bf16_f32 v129, v129, v130
	s_waitcnt lgkmcnt(6)
	v_mfma_f32_32x32x16_bf16 v[16:31], v[152:155], v[184:187], v[16:31]
	ds_read_b64_tr_b16 v[156:157], v160 offset:45184
	ds_read_b64_tr_b16 v[158:159], v160 offset:47744
	ds_read_b64_tr_b16 v[180:181], v160 offset:45248
	ds_read_b64_tr_b16 v[182:183], v160 offset:47808
	v_exp_f32_e32 v130, v132
	v_exp_f32_e32 v131, v133
	s_nop 0
	v_add_f32_e32 v172, v130, v131
	v_cvt_pk_bf16_f32 v130, v130, v131
	s_waitcnt lgkmcnt(8)
	v_mfma_f32_32x32x16_bf16 v[0:15], v[152:155], v[188:191], v[0:15]
	v_exp_f32_e32 v131, v134
	v_exp_f32_e32 v132, v135
	s_nop 0
	v_add_f32_e32 v173, v131, v132
	v_cvt_pk_bf16_f32 v131, v131, v132
	s_setprio 0
	s_setprio 1
	s_waitcnt lgkmcnt(6)
	v_mfma_f32_32x32x16_bf16 v[48:63], v[128:131], v[144:147], v[48:63]
	ds_read_b64_tr_b16 v[132:133], v160 offset:50176
	ds_read_b64_tr_b16 v[134:135], v160 offset:52736
	ds_read_b64_tr_b16 v[144:145], v160 offset:50240
	ds_read_b64_tr_b16 v[146:147], v160 offset:52800
	v_exp_f32_e32 v136, v136
	v_exp_f32_e32 v137, v137
	s_nop 0
	v_add_f32_e32 v184, v136, v137
	v_cvt_pk_bf16_f32 v136, v136, v137
	s_waitcnt lgkmcnt(8)
	v_mfma_f32_32x32x16_bf16 v[32:47], v[128:131], v[148:151], v[32:47]
	v_exp_f32_e32 v137, v138
	v_exp_f32_e32 v138, v139
	s_nop 0
	v_add_f32_e32 v185, v137, v138
	v_cvt_pk_bf16_f32 v137, v137, v138
	s_waitcnt lgkmcnt(6)
	v_mfma_f32_32x32x16_bf16 v[16:31], v[128:131], v[156:159], v[16:31]
	ds_read_b64_tr_b16 v[148:149], v160 offset:50304
	ds_read_b64_tr_b16 v[150:151], v160 offset:52864
	ds_read_b64_tr_b16 v[152:153], v160 offset:50368
	ds_read_b64_tr_b16 v[154:155], v160 offset:52928
	v_exp_f32_e32 v138, v140
	v_exp_f32_e32 v139, v141
	s_nop 0
	v_add_f32_e32 v140, v138, v139
	v_cvt_pk_bf16_f32 v138, v138, v139
	s_waitcnt lgkmcnt(8)
	v_mfma_f32_32x32x16_bf16 v[0:15], v[128:131], v[180:183], v[0:15]
	v_exp_f32_e32 v128, v142
	v_exp_f32_e32 v129, v143
	s_nop 0
	v_add_f32_e32 v131, v128, v129
	v_cvt_pk_bf16_f32 v139, v128, v129
	s_setprio 0
	v_add_f32_e32 v128, v176, v174
	v_add_f32_e32 v128, v177, v128
	v_add_f32_e32 v128, v178, v128
	v_add_f32_e32 v130, v179, v128
	v_add_f32_e32 v128, v175, v162
	v_add_f32_e32 v128, v163, v128
	v_add_f32_e32 v128, v164, v128
	v_add_f32_e32 v128, v165, v128
	v_add_f32_e32 v128, v166, v128
	v_add_f32_e32 v128, v167, v128
	v_add_f32_e32 v128, v168, v128
	v_add_f32_e32 v128, v169, v128
	s_waitcnt lgkmcnt(6)
	v_mfma_f32_32x32x16_bf16 v[48:63], v[136:139], v[132:135], v[48:63]
	v_add_f32_e32 v128, v170, v128
	v_add_f32_e32 v128, v171, v128
	v_add_f32_e32 v128, v172, v128
	v_add_f32_e32 v128, v173, v128
	v_add_f32_e32 v128, v184, v128
	v_add_f32_e32 v128, v185, v128
	v_add_f32_e32 v128, v140, v128
	s_waitcnt lgkmcnt(4)
	v_mfma_f32_32x32x16_bf16 v[32:47], v[136:139], v[144:147], v[32:47]
	v_add_f32_e32 v131, v131, v128
	s_waitcnt lgkmcnt(2)
	v_mfma_f32_32x32x16_bf16 v[16:31], v[136:139], v[148:151], v[16:31]
	s_waitcnt lgkmcnt(0)
	v_mfma_f32_32x32x16_bf16 v[0:15], v[136:139], v[152:155], v[0:15]
	v_mov_b32_e32 v129, v218
	s_waitcnt vmcnt(0)
	s_barrier
	s_nop 0
	v_and_b32_e32 v128, 63, v129
	v_lshlrev_b32_e32 v139, 2, v128
	v_xor_b32_e32 v133, 0x80, v139
	ds_bpermute_b32 v132, v133, v130
	ds_bpermute_b32 v133, v133, v131
	v_and_b32_e32 v138, 31, v129
	v_cmp_gt_u32_e32 vcc, 32, v128
	s_and_saveexec_b64 s[6:7], vcc
	s_cbranch_execz .LBB0_111
	s_waitcnt lgkmcnt(0)
	v_add_f32_e32 v131, v131, v133
	v_add_f32_e32 v130, v130, v132
	v_lshl_add_u32 v132, v138, 2, s91
	ds_write2_b32 v132, v130, v131 offset1:32
	s_branch .LBB0_111
